# grid barrier: XCD leader releases per-XCD generation before its own L1 invalidate (11 sites)
# baseline (speedup 1.0000x reference)
; __device__ __forceinline__ unsigned xb_ld(unsigned* p)              { return __hip_atomic_load(p, __ATOMIC_RELAXED, __HIP_MEMORY_SCOPE_AGENT); }
; __device__ __forceinline__ unsigned xb_add(unsigned* p, unsigned v) { return __hip_atomic_fetch_add(p, v, __ATOMIC_RELAXED, __HIP_MEMORY_SCOPE_AGENT); }
; #define XB_SPIN(cond, bar) do { unsigned _sp = 0; while (cond) { __builtin_amdgcn_s_sleep(1); \
;     if ((++_sp & 255u) == 0u) { if (xb_ld(&(bar)[XB_TMO])) break; if (_sp > XB_SPIN_CAP) { atomicAdd(&(bar)[XB_TMO], 1u); break; } } } } while (0)
; __device__ __forceinline__ void xcd_barrier(unsigned char* ws_base, volatile LAS unsigned* st) {
;     ...
;             __builtin_amdgcn_fence(__ATOMIC_RELEASE, "agent");
;             asm volatile("s_waitcnt vmcnt(0)" ::: "memory");
;             const unsigned og = xb_add(&bar[XB_TOP], 1u);
;             const unsigned tg = og / nx;
;             if (og + 1u == (tg + 1u) * nx) xb_add(&bar[XB_TOPGEN], 1u);
;             else XB_SPIN(xb_ld(&bar[XB_TOPGEN]) == tg, bar);
;             __builtin_amdgcn_fence(__ATOMIC_ACQUIRE, "agent");
;             xb_add(&bar[XB_XGEN(x)], 1u);
;             asm volatile("s_waitcnt vmcnt(0)" ::: "memory");
.LBB0_21:
	s_or_b64 exec, exec, s[0:1]
	v_mov_b32_e32 v0, s13
	v_add_co_u32_e32 v0, vcc, 0x2000, v0
	v_mov_b32_e32 v1, s12
	s_nop 0
	v_addc_co_u32_e32 v1, vcc, 0, v1, vcc
	v_mov_b32_e32 v2, 1
	s_waitcnt vmcnt(0) lgkmcnt(0)
	flat_atomic_add v[0:1], v2 offset:1024
	buffer_inv sc1
	s_waitcnt vmcnt(0)

; __device__ __forceinline__ unsigned xb_ld(unsigned* p)              { return __hip_atomic_load(p, __ATOMIC_RELAXED, __HIP_MEMORY_SCOPE_AGENT); }
; __device__ __forceinline__ unsigned xb_add(unsigned* p, unsigned v) { return __hip_atomic_fetch_add(p, v, __ATOMIC_RELAXED, __HIP_MEMORY_SCOPE_AGENT); }
; #define XB_SPIN(cond, bar) do { unsigned _sp = 0; while (cond) { __builtin_amdgcn_s_sleep(1); \
;     if ((++_sp & 255u) == 0u) { if (xb_ld(&(bar)[XB_TMO])) break; if (_sp > XB_SPIN_CAP) { atomicAdd(&(bar)[XB_TMO], 1u); break; } } } } while (0)
; __device__ __forceinline__ void xcd_barrier(unsigned char* ws_base, volatile LAS unsigned* st) {
;     ...
;             __builtin_amdgcn_fence(__ATOMIC_RELEASE, "agent");
;             asm volatile("s_waitcnt vmcnt(0)" ::: "memory");
;             const unsigned og = xb_add(&bar[XB_TOP], 1u);
;             const unsigned tg = og / nx;
;             if (og + 1u == (tg + 1u) * nx) xb_add(&bar[XB_TOPGEN], 1u);
;             else XB_SPIN(xb_ld(&bar[XB_TOPGEN]) == tg, bar);
;             __builtin_amdgcn_fence(__ATOMIC_ACQUIRE, "agent");
;             xb_add(&bar[XB_XGEN(x)], 1u);
;             asm volatile("s_waitcnt vmcnt(0)" ::: "memory");
.LBB0_287:
	s_or_b64 exec, exec, s[0:1]
	v_mov_b32_e32 v0, s5
	v_add_co_u32_e32 v0, vcc, 0x2000, v0
	v_mov_b32_e32 v1, s4
	s_nop 0
	v_addc_co_u32_e32 v1, vcc, 0, v1, vcc
	v_mov_b32_e32 v2, 1
	s_waitcnt vmcnt(0) lgkmcnt(0)
	flat_atomic_add v[0:1], v2 offset:1024
	buffer_inv sc1
	s_waitcnt vmcnt(0)
